# GDN state update: K operands streamed 12 LDS reads ahead of the f32 MFMAs
# speedup vs baseline: 1.0120x; 1.0037x over previous
; #define MFMA16F(a, b, c) __builtin_amdgcn_mfma_f32_16x16x4f32((a), (b), (c), 0, 0, 0)
; DI void gdn_scan_block(LAS unsigned char* lds, int c, const float* P, const GdnPar& pr, float* ORAW, int tid, int lane, int wave) {
;     ...
;             for (int tb = 0; tb < 2; ++tb) { f32x4 o;
; #pragma unroll
;                 for (int i = 0; i < 4; ++i) o[i] = PQa[tb][i] * __expf(GC_[16 * tb + 4 * g + i]);
; #pragma unroll
;                 for (int js = 0; js < 8; ++js) o = MFMA16F(M2[(16 * tb + m) * 33 + 4 * js + g], bC[js], o);
; #pragma unroll
;                 for (int i = 0; i < 4; ++i) ORAW[(tok_base + cidx * 32 + 16 * tb + 4 * g + i) * MIXW + vh * 128 + half * 64 + cw16 + m] = o[i]; }
;             const float e31 = __expf(GC_[31]);
;             float ej[8];
; #pragma unroll
;             for (int js = 0; js < 8; ++js) ej[js] = E31_[4 * js + g];
; #pragma unroll
;             for (int kb8 = 0; kb8 < 8; ++kb8) { f32x4 acc = Sacc[kb8] * e31;
; #pragma unroll
;                 for (int js = 0; js < 8; ++js) acc = MFMA16F(K_[(4 * js + g) * KP + 16 * kb8 + m] * ej[js], bC[js], acc);
;                 Sacc[kb8] = acc; }
.LBB0_888:
	s_or_b64 exec, exec, s[34:35]
	s_waitcnt lgkmcnt(0)
	v_add_u32_e32 v80, 0xa500, v125
	v_add_u32_e32 v100, 0xa508, v125
	ds_read2st64_b32 v[78:79], v134 offset1:4
	ds_read2st64_b32 v[76:77], v134 offset0:8 offset1:12
	ds_read2st64_b32 v[74:75], v134 offset0:16 offset1:20
	ds_read2st64_b32 v[72:73], v134 offset0:24 offset1:28
	ds_read2_b32 v[80:81], v80 offset1:1
	ds_read2_b32 v[100:101], v100 offset1:1
	v_add_u32_e32 v106, 0xd400, v186
	s_mov_b32 s0, 0x2ea00000
	v_add_u32_e32 v128, 0x4000, v148
	s_waitcnt lgkmcnt(1)
	v_mul_f32_e32 v80, 0x3fb8aa3b, v80
	v_mul_f32_e32 v81, 0x3fb8aa3b, v81
	s_waitcnt lgkmcnt(0)
	v_mul_f32_e32 v100, 0x3fb8aa3b, v100
	v_mul_f32_e32 v101, 0x3fb8aa3b, v101
	v_exp_f32_e32 v80, v80
	v_exp_f32_e32 v81, v81
	v_exp_f32_e32 v100, v100
	v_exp_f32_e32 v101, v101
	v_add_u32_e32 v189, 0x4800, v148
	v_add_u32_e32 v204, 0x5000, v148
	v_add_u32_e32 v205, 0x5800, v148
	v_pk_mul_f32 v[102:103], v[66:67], v[100:101]
	v_pk_mul_f32 v[100:101], v[64:65], v[80:81]
	ds_read2_b32 v[80:81], v106 offset0:192 offset1:196
	ds_read2_b32 v[104:105], v106 offset0:200 offset1:204
	s_waitcnt lgkmcnt(1)
	v_mfma_f32_16x16x4_f32 v[100:103], v80, v78, v[100:103]
	v_add_u32_e32 v208, 0x6000, v148
	v_mfma_f32_16x16x4_f32 v[100:103], v81, v79, v[100:103]
	ds_read2_b32 v[80:81], v106 offset0:208 offset1:212
	s_waitcnt lgkmcnt(1)
	v_mfma_f32_16x16x4_f32 v[100:103], v104, v76, v[100:103]
	v_mfma_f32_16x16x4_f32 v[100:103], v105, v77, v[100:103]
	s_waitcnt lgkmcnt(0)
	v_mfma_f32_16x16x4_f32 v[100:103], v80, v74, v[100:103]
	v_mfma_f32_16x16x4_f32 v[100:103], v81, v75, v[100:103]
	ds_read2_b32 v[80:81], v106 offset0:216 offset1:220
	v_add_u32_e32 v106, 0xdc00, v186
	s_waitcnt lgkmcnt(0)
	v_mfma_f32_16x16x4_f32 v[100:103], v80, v72, v[100:103]
	v_mfma_f32_16x16x4_f32 v[100:103], v81, v73, v[100:103]
	v_lshl_add_u64 v[80:81], s[40:41], 0, v[96:97]
	v_add_co_u32_e32 v104, vcc, s0, v80
	s_mov_b32 s0, 0x2ea01000
	s_nop 0
	v_addc_co_u32_e32 v105, vcc, 0, v81, vcc
	s_nop 4
	global_store_dword v[104:105], v100, off
	v_add_co_u32_e32 v104, vcc, s0, v80
	s_mov_b32 s0, 0x2ea03000
	s_nop 0
	v_addc_co_u32_e32 v105, vcc, 0, v81, vcc
	v_add_co_u32_e32 v100, vcc, s0, v80
	global_store_dword v[104:105], v101, off offset:2048
	s_nop 0
	v_addc_co_u32_e32 v101, vcc, 0, v81, vcc
	s_mov_b32 s0, 0x2ea04000
	v_add_co_u32_e32 v80, vcc, s0, v80
	global_store_dword v[100:101], v102, off
	s_nop 0
	v_addc_co_u32_e32 v81, vcc, 0, v81, vcc
	global_store_dword v[80:81], v103, off offset:2048
	v_add_u32_e32 v80, 0xa540, v125
	v_add_u32_e32 v100, 0xa548, v125
	ds_read2_b32 v[80:81], v80 offset1:1
	ds_read2_b32 v[100:101], v100 offset1:1
	s_mov_b32 s0, 0x2ea18000
	s_waitcnt lgkmcnt(1)
	v_mul_f32_e32 v80, 0x3fb8aa3b, v80
	v_mul_f32_e32 v81, 0x3fb8aa3b, v81
	s_waitcnt lgkmcnt(0)
	v_mul_f32_e32 v100, 0x3fb8aa3b, v100
	v_mul_f32_e32 v101, 0x3fb8aa3b, v101
	v_exp_f32_e32 v80, v80
	v_exp_f32_e32 v81, v81
	v_exp_f32_e32 v100, v100
	v_exp_f32_e32 v101, v101
	s_nop 0
	v_pk_mul_f32 v[102:103], v[70:71], v[100:101]
	v_pk_mul_f32 v[100:101], v[68:69], v[80:81]
	ds_read2_b32 v[80:81], v106 offset0:208 offset1:212
	ds_read2_b32 v[104:105], v106 offset0:216 offset1:220
	s_waitcnt lgkmcnt(1)
	v_mfma_f32_16x16x4_f32 v[100:103], v80, v78, v[100:103]
	v_mfma_f32_16x16x4_f32 v[100:103], v81, v79, v[100:103]
	ds_read2_b32 v[80:81], v106 offset0:224 offset1:228
	s_waitcnt lgkmcnt(1)
	v_mfma_f32_16x16x4_f32 v[100:103], v104, v76, v[100:103]
	v_mfma_f32_16x16x4_f32 v[100:103], v105, v77, v[100:103]
	s_waitcnt lgkmcnt(0)
	v_mfma_f32_16x16x4_f32 v[100:103], v80, v74, v[100:103]
	v_mfma_f32_16x16x4_f32 v[100:103], v81, v75, v[100:103]
	ds_read2_b32 v[80:81], v106 offset0:232 offset1:236
	s_waitcnt lgkmcnt(0)
	v_mfma_f32_16x16x4_f32 v[100:103], v80, v72, v[100:103]
	v_mfma_f32_16x16x4_f32 v[100:103], v81, v73, v[100:103]
	v_lshl_add_u64 v[80:81], s[40:41], 0, v[94:95]
	v_add_co_u32_e32 v104, vcc, s0, v80
	s_mov_b32 s0, 0x2ea19000
	s_nop 0
	v_addc_co_u32_e32 v105, vcc, 0, v81, vcc
	s_nop 4
	global_store_dword v[104:105], v100, off
	v_add_co_u32_e32 v104, vcc, s0, v80
	s_mov_b32 s0, 0x2ea1b000
	s_nop 0
	v_addc_co_u32_e32 v105, vcc, 0, v81, vcc
	v_add_co_u32_e32 v100, vcc, s0, v80
	global_store_dword v[104:105], v101, off offset:2048
	s_nop 0
	v_addc_co_u32_e32 v101, vcc, 0, v81, vcc
	s_mov_b32 s0, 0x2ea1c000
	v_add_co_u32_e32 v80, vcc, s0, v80
	global_store_dword v[100:101], v102, off
	s_nop 0
	v_addc_co_u32_e32 v81, vcc, 0, v81, vcc
	global_store_dword v[80:81], v103, off offset:2048
	v_mov_b32_e32 v80, s78
	ds_read_b32 v80, v80 offset:42364
	ds_read_b32 v56, v135 offset:42368
	ds_read_b32 v57, v135 offset:42384
	ds_read_b32 v58, v135 offset:42400
	ds_read_b32 v59, v135 offset:42416
	ds_read_b32 v60, v135 offset:42432
	ds_read_b32 v61, v135 offset:42448
	ds_read_b32 v62, v135 offset:42464
	ds_read_b32 v63, v135 offset:42480
	ds_read_b32 v189, v148 offset:16896
	ds_read_b32 v190, v148 offset:19008
	ds_read_b32 v191, v148 offset:21120
	ds_read_b32 v192, v148 offset:23232
	ds_read_b32 v193, v148 offset:25344
	ds_read_b32 v194, v148 offset:27456
	s_waitcnt lgkmcnt(14)
	v_mul_f32_e32 v106, 0x3fb8aa3b, v80
	v_exp_f32_e32 v106, v106
	ds_read_b32 v195, v148 offset:29568
	ds_read_b32 v196, v148 offset:31680
	ds_read_b32 v197, v148 offset:16960
	ds_read_b32 v198, v148 offset:19072
	ds_read_b32 v199, v148 offset:21184
	ds_read_b32 v200, v148 offset:23296
	s_waitcnt lgkmcnt(12)
	v_pk_mul_f32 v[48:49], v[48:49], v[106:107] op_sel_hi:[1,0]
	v_pk_mul_f32 v[50:51], v[50:51], v[106:107] op_sel_hi:[1,0]
	ds_read_b32 v201, v148 offset:25408
	s_waitcnt lgkmcnt(12)
	v_mul_f32_e32 v205, v189, v56
	ds_read_b32 v202, v148 offset:27520
	s_waitcnt lgkmcnt(12)
; #define MFMA16F(a, b, c) __builtin_amdgcn_mfma_f32_16x16x4f32((a), (b), (c), 0, 0, 0)
; DI void gdn_scan_block(LAS unsigned char* lds, int c, const float* P, const GdnPar& pr, float* ORAW, int tid, int lane, int wave) {
;     ...
;             const float e31 = __expf(GC_[31]);
;             float ej[8];
; #pragma unroll
;             for (int js = 0; js < 8; ++js) ej[js] = E31_[4 * js + g];
; #pragma unroll
;             for (int kb8 = 0; kb8 < 8; ++kb8) { f32x4 acc = Sacc[kb8] * e31;
; #pragma unroll
;                 for (int js = 0; js < 8; ++js) acc = MFMA16F(K_[(4 * js + g) * KP + 16 * kb8 + m] * ej[js], bC[js], acc);
;                 Sacc[kb8] = acc; }
	v_mul_f32_e32 v208, v190, v57
	v_mfma_f32_16x16x4_f32 v[48:51], v205, v78, v[48:51]
	ds_read_b32 v203, v148 offset:29632
	s_waitcnt lgkmcnt(12)
	v_mul_f32_e32 v205, v191, v58
	v_mfma_f32_16x16x4_f32 v[48:51], v208, v79, v[48:51]
	ds_read_b32 v204, v148 offset:31744
	s_waitcnt lgkmcnt(12)
	v_mul_f32_e32 v208, v192, v59
	v_mfma_f32_16x16x4_f32 v[48:51], v205, v76, v[48:51]
	ds_read_b32 v189, v148 offset:17024
	s_waitcnt lgkmcnt(12)
	v_mul_f32_e32 v205, v193, v60
	v_mfma_f32_16x16x4_f32 v[48:51], v208, v77, v[48:51]
	ds_read_b32 v190, v148 offset:19136
	s_waitcnt lgkmcnt(12)
	v_mul_f32_e32 v208, v194, v61
	v_mfma_f32_16x16x4_f32 v[48:51], v205, v74, v[48:51]
	ds_read_b32 v191, v148 offset:21248
	s_waitcnt lgkmcnt(12)
	v_mul_f32_e32 v205, v195, v62
	v_mfma_f32_16x16x4_f32 v[48:51], v208, v75, v[48:51]
	ds_read_b32 v192, v148 offset:23360
	s_waitcnt lgkmcnt(12)
	v_mul_f32_e32 v208, v196, v63
	v_mfma_f32_16x16x4_f32 v[48:51], v205, v72, v[48:51]
	v_pk_mul_f32 v[24:25], v[24:25], v[106:107] op_sel_hi:[1,0]
	v_pk_mul_f32 v[26:27], v[26:27], v[106:107] op_sel_hi:[1,0]
	ds_read_b32 v193, v148 offset:25472
	s_waitcnt lgkmcnt(12)
	v_mul_f32_e32 v205, v197, v56
	v_mfma_f32_16x16x4_f32 v[48:51], v208, v73, v[48:51]
	ds_read_b32 v194, v148 offset:27584
	s_waitcnt lgkmcnt(12)
	v_mul_f32_e32 v208, v198, v57
	v_mfma_f32_16x16x4_f32 v[24:27], v205, v78, v[24:27]
	ds_read_b32 v195, v148 offset:29696
	s_waitcnt lgkmcnt(12)
	v_mul_f32_e32 v205, v199, v58
	v_mfma_f32_16x16x4_f32 v[24:27], v208, v79, v[24:27]
	ds_read_b32 v196, v148 offset:31808
	s_waitcnt lgkmcnt(12)
	v_mul_f32_e32 v208, v200, v59
	v_mfma_f32_16x16x4_f32 v[24:27], v205, v76, v[24:27]
	ds_read_b32 v197, v148 offset:17088
	s_waitcnt lgkmcnt(12)
	v_mul_f32_e32 v205, v201, v60
	v_mfma_f32_16x16x4_f32 v[24:27], v208, v77, v[24:27]
	ds_read_b32 v198, v148 offset:19200
	s_waitcnt lgkmcnt(12)
	v_mul_f32_e32 v208, v202, v61
	v_mfma_f32_16x16x4_f32 v[24:27], v205, v74, v[24:27]
	ds_read_b32 v199, v148 offset:21312
	s_waitcnt lgkmcnt(12)
	v_mul_f32_e32 v205, v203, v62
	v_mfma_f32_16x16x4_f32 v[24:27], v208, v75, v[24:27]
	ds_read_b32 v200, v148 offset:23424
	s_waitcnt lgkmcnt(12)
	v_mul_f32_e32 v208, v204, v63
	v_mfma_f32_16x16x4_f32 v[24:27], v205, v72, v[24:27]
	v_pk_mul_f32 v[36:37], v[36:37], v[106:107] op_sel_hi:[1,0]
	v_pk_mul_f32 v[38:39], v[38:39], v[106:107] op_sel_hi:[1,0]
	ds_read_b32 v201, v148 offset:25536
	s_waitcnt lgkmcnt(12)
	v_mul_f32_e32 v205, v189, v56
	v_mfma_f32_16x16x4_f32 v[24:27], v208, v73, v[24:27]
	ds_read_b32 v202, v148 offset:27648
	s_waitcnt lgkmcnt(12)
	v_mul_f32_e32 v208, v190, v57
	v_mfma_f32_16x16x4_f32 v[36:39], v205, v78, v[36:39]
	ds_read_b32 v203, v148 offset:29760
	s_waitcnt lgkmcnt(12)
	v_mul_f32_e32 v205, v191, v58
	v_mfma_f32_16x16x4_f32 v[36:39], v208, v79, v[36:39]
	ds_read_b32 v204, v148 offset:31872
	s_waitcnt lgkmcnt(12)
	v_mul_f32_e32 v208, v192, v59
	v_mfma_f32_16x16x4_f32 v[36:39], v205, v76, v[36:39]
	ds_read_b32 v189, v148 offset:17152
	s_waitcnt lgkmcnt(12)
	v_mul_f32_e32 v205, v193, v60
	v_mfma_f32_16x16x4_f32 v[36:39], v208, v77, v[36:39]
	ds_read_b32 v190, v148 offset:19264
	s_waitcnt lgkmcnt(12)
	v_mul_f32_e32 v208, v194, v61
	v_mfma_f32_16x16x4_f32 v[36:39], v205, v74, v[36:39]
	ds_read_b32 v191, v148 offset:21376
	s_waitcnt lgkmcnt(12)
	v_mul_f32_e32 v205, v195, v62
	v_mfma_f32_16x16x4_f32 v[36:39], v208, v75, v[36:39]
	ds_read_b32 v192, v148 offset:23488
	s_waitcnt lgkmcnt(12)
	v_mul_f32_e32 v208, v196, v63
	v_mfma_f32_16x16x4_f32 v[36:39], v205, v72, v[36:39]
	v_pk_mul_f32 v[28:29], v[28:29], v[106:107] op_sel_hi:[1,0]
	v_pk_mul_f32 v[30:31], v[30:31], v[106:107] op_sel_hi:[1,0]
	ds_read_b32 v193, v148 offset:25600
	s_waitcnt lgkmcnt(12)
	v_mul_f32_e32 v205, v197, v56
	v_mfma_f32_16x16x4_f32 v[36:39], v208, v73, v[36:39]
	ds_read_b32 v194, v148 offset:27712
	s_waitcnt lgkmcnt(12)
	v_mul_f32_e32 v208, v198, v57
	v_mfma_f32_16x16x4_f32 v[28:31], v205, v78, v[28:31]
	ds_read_b32 v195, v148 offset:29824
	s_waitcnt lgkmcnt(12)
	v_mul_f32_e32 v205, v199, v58
	v_mfma_f32_16x16x4_f32 v[28:31], v208, v79, v[28:31]
	ds_read_b32 v196, v148 offset:31936
	s_waitcnt lgkmcnt(12)
	v_mul_f32_e32 v208, v200, v59
	v_mfma_f32_16x16x4_f32 v[28:31], v205, v76, v[28:31]
	ds_read_b32 v197, v148 offset:17216
	s_waitcnt lgkmcnt(12)
	v_mul_f32_e32 v205, v201, v60
	v_mfma_f32_16x16x4_f32 v[28:31], v208, v77, v[28:31]
	ds_read_b32 v198, v148 offset:19328
	s_waitcnt lgkmcnt(12)
	v_mul_f32_e32 v208, v202, v61
	v_mfma_f32_16x16x4_f32 v[28:31], v205, v74, v[28:31]
	ds_read_b32 v199, v148 offset:21440
	s_waitcnt lgkmcnt(12)
	v_mul_f32_e32 v205, v203, v62
	v_mfma_f32_16x16x4_f32 v[28:31], v208, v75, v[28:31]
	ds_read_b32 v200, v148 offset:23552
	s_waitcnt lgkmcnt(12)
; #define MFMA16F(a, b, c) __builtin_amdgcn_mfma_f32_16x16x4f32((a), (b), (c), 0, 0, 0)
; DI void gdn_scan_block(LAS unsigned char* lds, int c, const float* P, const GdnPar& pr, float* ORAW, int tid, int lane, int wave) {
;     ...
;             const float e31 = __expf(GC_[31]);
;             float ej[8];
; #pragma unroll
;             for (int js = 0; js < 8; ++js) ej[js] = E31_[4 * js + g];
; #pragma unroll
;             for (int kb8 = 0; kb8 < 8; ++kb8) { f32x4 acc = Sacc[kb8] * e31;
; #pragma unroll
;                 for (int js = 0; js < 8; ++js) acc = MFMA16F(K_[(4 * js + g) * KP + 16 * kb8 + m] * ej[js], bC[js], acc);
;                 Sacc[kb8] = acc; }
	v_mul_f32_e32 v208, v204, v63
	v_mfma_f32_16x16x4_f32 v[28:31], v205, v72, v[28:31]
	v_pk_mul_f32 v[40:41], v[40:41], v[106:107] op_sel_hi:[1,0]
	v_pk_mul_f32 v[42:43], v[42:43], v[106:107] op_sel_hi:[1,0]
	ds_read_b32 v201, v148 offset:25664
	s_waitcnt lgkmcnt(12)
	v_mul_f32_e32 v205, v189, v56
	v_mfma_f32_16x16x4_f32 v[28:31], v208, v73, v[28:31]
	ds_read_b32 v202, v148 offset:27776
	s_waitcnt lgkmcnt(12)
	v_mul_f32_e32 v208, v190, v57
	v_mfma_f32_16x16x4_f32 v[40:43], v205, v78, v[40:43]
	ds_read_b32 v203, v148 offset:29888
	s_waitcnt lgkmcnt(12)
	v_mul_f32_e32 v205, v191, v58
	v_mfma_f32_16x16x4_f32 v[40:43], v208, v79, v[40:43]
	ds_read_b32 v204, v148 offset:32000
	s_waitcnt lgkmcnt(12)
	v_mul_f32_e32 v208, v192, v59
	v_mfma_f32_16x16x4_f32 v[40:43], v205, v76, v[40:43]
	ds_read_b32 v189, v148 offset:17280
	s_waitcnt lgkmcnt(12)
	v_mul_f32_e32 v205, v193, v60
	v_mfma_f32_16x16x4_f32 v[40:43], v208, v77, v[40:43]
	ds_read_b32 v190, v148 offset:19392
	s_waitcnt lgkmcnt(12)
	v_mul_f32_e32 v208, v194, v61
	v_mfma_f32_16x16x4_f32 v[40:43], v205, v74, v[40:43]
	ds_read_b32 v191, v148 offset:21504
	s_waitcnt lgkmcnt(12)
	v_mul_f32_e32 v205, v195, v62
	v_mfma_f32_16x16x4_f32 v[40:43], v208, v75, v[40:43]
	ds_read_b32 v192, v148 offset:23616
	s_waitcnt lgkmcnt(12)
	v_mul_f32_e32 v208, v196, v63
	v_mfma_f32_16x16x4_f32 v[40:43], v205, v72, v[40:43]
	v_pk_mul_f32 v[32:33], v[32:33], v[106:107] op_sel_hi:[1,0]
	v_pk_mul_f32 v[34:35], v[34:35], v[106:107] op_sel_hi:[1,0]
	ds_read_b32 v193, v148 offset:25728
	s_waitcnt lgkmcnt(12)
	v_mul_f32_e32 v205, v197, v56
	v_mfma_f32_16x16x4_f32 v[40:43], v208, v73, v[40:43]
	ds_read_b32 v194, v148 offset:27840
	s_waitcnt lgkmcnt(12)
	v_mul_f32_e32 v208, v198, v57
	v_mfma_f32_16x16x4_f32 v[32:35], v205, v78, v[32:35]
	ds_read_b32 v195, v148 offset:29952
	s_waitcnt lgkmcnt(12)
	v_mul_f32_e32 v205, v199, v58
	v_mfma_f32_16x16x4_f32 v[32:35], v208, v79, v[32:35]
	ds_read_b32 v196, v148 offset:32064
	s_waitcnt lgkmcnt(12)
	v_mul_f32_e32 v208, v200, v59
	v_mfma_f32_16x16x4_f32 v[32:35], v205, v76, v[32:35]
	ds_read_b32 v197, v148 offset:17344
	s_waitcnt lgkmcnt(12)
	v_mul_f32_e32 v205, v201, v60
	v_mfma_f32_16x16x4_f32 v[32:35], v208, v77, v[32:35]
	ds_read_b32 v198, v148 offset:19456
	s_waitcnt lgkmcnt(12)
	v_mul_f32_e32 v208, v202, v61
	v_mfma_f32_16x16x4_f32 v[32:35], v205, v74, v[32:35]
	ds_read_b32 v199, v148 offset:21568
	s_waitcnt lgkmcnt(12)
	v_mul_f32_e32 v205, v203, v62
	v_mfma_f32_16x16x4_f32 v[32:35], v208, v75, v[32:35]
	ds_read_b32 v200, v148 offset:23680
	s_waitcnt lgkmcnt(12)
	v_mul_f32_e32 v208, v204, v63
	v_mfma_f32_16x16x4_f32 v[32:35], v205, v72, v[32:35]
	v_pk_mul_f32 v[44:45], v[44:45], v[106:107] op_sel_hi:[1,0]
	v_pk_mul_f32 v[46:47], v[46:47], v[106:107] op_sel_hi:[1,0]
	ds_read_b32 v201, v148 offset:25792
	s_waitcnt lgkmcnt(12)
	v_mul_f32_e32 v205, v189, v56
	v_mfma_f32_16x16x4_f32 v[32:35], v208, v73, v[32:35]
	ds_read_b32 v202, v148 offset:27904
	s_waitcnt lgkmcnt(12)
	v_mul_f32_e32 v208, v190, v57
	v_mfma_f32_16x16x4_f32 v[44:47], v205, v78, v[44:47]
	ds_read_b32 v203, v148 offset:30016
	s_waitcnt lgkmcnt(12)
	v_mul_f32_e32 v205, v191, v58
	v_mfma_f32_16x16x4_f32 v[44:47], v208, v79, v[44:47]
	ds_read_b32 v204, v148 offset:32128
	s_waitcnt lgkmcnt(12)
	v_mul_f32_e32 v208, v192, v59
	v_mfma_f32_16x16x4_f32 v[44:47], v205, v76, v[44:47]
	s_waitcnt lgkmcnt(11)
	v_mul_f32_e32 v205, v193, v60
	v_mfma_f32_16x16x4_f32 v[44:47], v208, v77, v[44:47]
	s_waitcnt lgkmcnt(10)
	v_mul_f32_e32 v208, v194, v61
	v_mfma_f32_16x16x4_f32 v[44:47], v205, v74, v[44:47]
	s_waitcnt lgkmcnt(9)
	v_mul_f32_e32 v205, v195, v62
	v_mfma_f32_16x16x4_f32 v[44:47], v208, v75, v[44:47]
	s_waitcnt lgkmcnt(8)
	v_mul_f32_e32 v208, v196, v63
	v_mfma_f32_16x16x4_f32 v[44:47], v205, v72, v[44:47]
	v_pk_mul_f32 v[52:53], v[52:53], v[106:107] op_sel_hi:[1,0]
	v_pk_mul_f32 v[54:55], v[54:55], v[106:107] op_sel_hi:[1,0]
	s_waitcnt lgkmcnt(7)
	v_mul_f32_e32 v205, v197, v56
	v_mfma_f32_16x16x4_f32 v[44:47], v208, v73, v[44:47]
	s_waitcnt lgkmcnt(6)
	v_mul_f32_e32 v208, v198, v57
	v_mfma_f32_16x16x4_f32 v[52:55], v205, v78, v[52:55]
	s_waitcnt lgkmcnt(5)
	v_mul_f32_e32 v205, v199, v58
	v_mfma_f32_16x16x4_f32 v[52:55], v208, v79, v[52:55]
	s_waitcnt lgkmcnt(4)
	v_mul_f32_e32 v208, v200, v59
	v_mfma_f32_16x16x4_f32 v[52:55], v205, v76, v[52:55]
	s_waitcnt lgkmcnt(3)
	v_mul_f32_e32 v205, v201, v60
	v_mfma_f32_16x16x4_f32 v[52:55], v208, v77, v[52:55]
	s_waitcnt lgkmcnt(2)
	v_mul_f32_e32 v208, v202, v61
	v_mfma_f32_16x16x4_f32 v[52:55], v205, v74, v[52:55]
	s_waitcnt lgkmcnt(1)
	v_mul_f32_e32 v205, v203, v62
	v_mfma_f32_16x16x4_f32 v[52:55], v208, v75, v[52:55]
	s_waitcnt lgkmcnt(0)
	v_mul_f32_e32 v208, v204, v63
	v_mfma_f32_16x16x4_f32 v[52:55], v205, v72, v[52:55]
	s_nop 1
	v_mfma_f32_16x16x4_f32 v[52:55], v208, v73, v[52:55]
